# attention tile loop: single lgkmcnt(0) before PV, next-tile LDS writes issued in the middle of the PV MFMAs, no per-fragment PV waits
# baseline (speedup 1.0000x reference)
.Lattn_sm:
	v_exp_f32_e32 v92, v92
	v_exp_f32_e32 v93, v93
	v_exp_f32_e32 v94, v94
	v_exp_f32_e32 v95, v95
	v_exp_f32_e32 v96, v96
	v_exp_f32_e32 v97, v97
	v_exp_f32_e32 v98, v98
	v_exp_f32_e32 v99, v99
	v_exp_f32_e32 v100, v100
	v_exp_f32_e32 v101, v101
	v_exp_f32_e32 v102, v102
	v_exp_f32_e32 v103, v103
	v_exp_f32_e32 v104, v104
	v_exp_f32_e32 v105, v105
	v_exp_f32_e32 v106, v106
	v_exp_f32_e32 v107, v107
	v_cvt_pk_bf16_f32 v92, v92, v93
	v_cvt_pk_bf16_f32 v93, v94, v95
	v_cvt_pk_bf16_f32 v94, v96, v97
	v_cvt_pk_bf16_f32 v95, v98, v99
	v_cvt_pk_bf16_f32 v96, v100, v101
	v_cvt_pk_bf16_f32 v97, v102, v103
	v_cvt_pk_bf16_f32 v98, v104, v105
	v_cvt_pk_bf16_f32 v99, v106, v107
	v_exp_f32_e32 v76, v76
	v_exp_f32_e32 v77, v77
	v_exp_f32_e32 v78, v78
	v_exp_f32_e32 v79, v79
	v_exp_f32_e32 v80, v80
	v_exp_f32_e32 v81, v81
	v_exp_f32_e32 v82, v82
	v_exp_f32_e32 v83, v83
	v_exp_f32_e32 v84, v84
	v_exp_f32_e32 v85, v85
	v_exp_f32_e32 v86, v86
	v_exp_f32_e32 v87, v87
	v_exp_f32_e32 v88, v88
	v_exp_f32_e32 v89, v89
	v_exp_f32_e32 v90, v90
	v_exp_f32_e32 v91, v91
	v_cvt_pk_bf16_f32 v76, v76, v77
	v_cvt_pk_bf16_f32 v77, v78, v79
	v_cvt_pk_bf16_f32 v78, v80, v81
	v_cvt_pk_bf16_f32 v79, v82, v83
	v_cvt_pk_bf16_f32 v80, v84, v85
	v_cvt_pk_bf16_f32 v81, v86, v87
	v_cvt_pk_bf16_f32 v82, v88, v89
	v_cvt_pk_bf16_f32 v83, v90, v91
	s_waitcnt lgkmcnt(0)
	v_mfma_f32_16x16x32_bf16 v[60:63], v[234:237], v[92:95], v[60:63]
	v_mfma_f32_16x16x32_bf16 v[56:59], v[234:237], v[76:79], v[56:59]
	v_mfma_f32_16x16x32_bf16 v[60:63], v[238:241], v[96:99], v[60:63]
	v_mfma_f32_16x16x32_bf16 v[56:59], v[238:241], v[80:83], v[56:59]
	v_mfma_f32_16x16x32_bf16 v[52:55], v[242:245], v[92:95], v[52:55]
	v_mfma_f32_16x16x32_bf16 v[48:51], v[242:245], v[76:79], v[48:51]
	v_mfma_f32_16x16x32_bf16 v[52:55], v[246:249], v[96:99], v[52:55]
	v_mfma_f32_16x16x32_bf16 v[48:51], v[246:249], v[80:83], v[48:51]
	s_add_i32 s7, s7, 1
	s_bitcmp1_b32 s7, 0
	s_cselect_b32 s2, 0x5c00, 0
	s_add_i32 s10, s2, 0
	v_add_u32_e32 v127, s10, v139
	v_add_u32_e32 v129, s10, v140
	v_add_u32_e32 v131, s10, v116
	s_waitcnt vmcnt(2)
	ds_write_b128 v127, v[72:75]
	s_waitcnt vmcnt(0)
	ds_write_b128 v131, v[64:67] offset:14336
	s_and_b64 vcc, exec, s[42:43]
	s_cbranch_vccz .Lattn_skipw
	ds_write_b128 v129, v[68:71]
.Lattn_skipw:
	v_mfma_f32_16x16x32_bf16 v[44:47], v[162:165], v[92:95], v[44:47]
	v_mfma_f32_16x16x32_bf16 v[40:43], v[162:165], v[76:79], v[40:43]
	v_mfma_f32_16x16x32_bf16 v[44:47], v[166:169], v[96:99], v[44:47]
	v_mfma_f32_16x16x32_bf16 v[40:43], v[166:169], v[80:83], v[40:43]
	v_mfma_f32_16x16x32_bf16 v[36:39], v[170:173], v[92:95], v[36:39]
	v_mfma_f32_16x16x32_bf16 v[32:35], v[170:173], v[76:79], v[32:35]
	v_mfma_f32_16x16x32_bf16 v[36:39], v[174:177], v[96:99], v[36:39]
	v_mfma_f32_16x16x32_bf16 v[32:35], v[174:177], v[80:83], v[32:35]
	v_mfma_f32_16x16x32_bf16 v[28:31], v[250:253], v[92:95], v[28:31]
	v_mfma_f32_16x16x32_bf16 v[24:27], v[250:253], v[76:79], v[24:27]
	v_mfma_f32_16x16x32_bf16 v[28:31], v[250:253], v[96:99], v[28:31]
	v_mfma_f32_16x16x32_bf16 v[24:27], v[250:253], v[80:83], v[24:27]
	v_add3_u32 v104, s10, v110, v142
	v_add3_u32 v147, s10, v138, v143
	v_lshl_add_u64 v[132:133], v[132:133], 0, s[50:51]
	v_lshl_add_u64 v[134:135], v[134:135], 0, s[4:5]
	v_lshl_add_u64 v[136:137], v[136:137], 0, s[4:5]
	s_cmp_eq_u32 s6, s7
	s_waitcnt lgkmcnt(0)
	s_cbranch_scc0 .LBB0_175
	s_barrier
	s_branch .LBB0_161
